# m11 + 88 aligned pairs of 32-bit register copies in the index phase fused into 64-bit moves
# speedup vs baseline: 1.0044x; 1.0041x over previous
.LBB0_1088:
	s_andn2_b64 vcc, exec, s[8:9]
	s_cbranch_vccnz .LBB0_1090
	v_mov_b64_e32 v[64:65], v[56:57]
	v_mov_b64_e32 v[62:63], v[54:55]

.LBB0_1091:
	s_andn2_b64 vcc, exec, s[8:9]
	s_cbranch_vccnz .LBB0_1095
	s_cmp_eq_u32 s61, 1
	s_cbranch_scc0 .LBB0_1094
	v_mov_b64_e32 v[64:65], v[48:49]
	v_mov_b64_e32 v[62:63], v[46:47]
	s_branch .LBB0_1095
.LBB0_1094:
	v_mov_b64_e32 v[64:65], v[12:13]
	v_mov_b64_e32 v[62:63], v[10:11]

.LBB0_1100:
	s_andn2_b64 vcc, exec, s[8:9]
	s_cbranch_vccnz .LBB0_1102
	v_mov_b64_e32 v[52:53], v[44:45]
	v_mov_b64_e32 v[50:51], v[42:43]

.LBB0_1103:
	s_andn2_b64 vcc, exec, s[8:9]
	s_cbranch_vccnz .LBB0_1107
	s_cmp_eq_u32 s61, 1
	s_cbranch_scc0 .LBB0_1106
	v_mov_b64_e32 v[52:53], v[36:37]
	v_mov_b64_e32 v[50:51], v[34:35]
	s_branch .LBB0_1107
.LBB0_1106:
	v_mov_b64_e32 v[52:53], v[40:41]
	v_mov_b64_e32 v[50:51], v[38:39]

.LBB0_1112:
	s_andn2_b64 vcc, exec, s[8:9]
	s_cbranch_vccnz .LBB0_1114
	v_mov_b64_e32 v[32:33], v[24:25]
	v_mov_b64_e32 v[30:31], v[22:23]

.LBB0_1115:
	s_andn2_b64 vcc, exec, s[8:9]
	s_cbranch_vccnz .LBB0_1119
	s_cmp_eq_u32 s61, 1
	s_cbranch_scc0 .LBB0_1118
	v_mov_b64_e32 v[32:33], v[12:13]
	v_mov_b64_e32 v[30:31], v[10:11]
	s_branch .LBB0_1119
.LBB0_1118:
	v_mov_b64_e32 v[32:33], v[16:17]
	v_mov_b64_e32 v[30:31], v[14:15]

.LBB0_1294:
	v_mov_b32_e32 v101, v250
	v_mov_b32_e32 v100, v249
	v_mov_b32_e32 v99, v248
	v_mov_b32_e32 v98, v247
	v_mov_b32_e32 v106, v246
	v_mov_b32_e32 v104, v245
	v_mov_b32_e32 v103, v244
	v_mov_b32_e32 v102, v243
	v_mov_b32_e32 v93, v242
	v_mov_b32_e32 v92, v241
	v_mov_b32_e32 v91, v240
	v_mov_b32_e32 v90, v239
	v_mov_b32_e32 v97, v238
	v_mov_b32_e32 v96, v237
	v_mov_b32_e32 v95, v236
	v_mov_b32_e32 v94, v235
	v_mov_b32_e32 v85, v234
	v_mov_b32_e32 v84, v233
	v_mov_b32_e32 v83, v232
	v_mov_b32_e32 v82, v231
	v_mov_b32_e32 v89, v230
	v_mov_b32_e32 v88, v229
	v_mov_b32_e32 v87, v228
	v_mov_b32_e32 v86, v227
	v_mov_b32_e32 v77, v226
	v_mov_b32_e32 v76, v225
	v_mov_b32_e32 v75, v218
	v_mov_b32_e32 v74, v216
	v_mov_b32_e32 v81, v214
	v_mov_b32_e32 v80, v212
	v_mov_b32_e32 v79, v210
	v_mov_b32_e32 v78, v208
	v_mov_b32_e32 v69, v219
	v_mov_b32_e32 v68, v217
	v_mov_b32_e32 v67, v215
	v_mov_b32_e32 v66, v213
	v_mov_b32_e32 v73, v211
	v_mov_b32_e32 v72, v209
	v_mov_b64_e32 v[70:71], v[206:207]
	v_mov_b64_e32 v[60:61], v[204:205]
	v_mov_b64_e32 v[58:59], v[202:203]
	v_mov_b64_e32 v[64:65], v[200:201]
	v_mov_b32_e32 v63, v188
	v_mov_b32_e32 v62, v185
	v_mov_b32_e32 v53, v184
	v_mov_b32_e32 v52, v183
	v_mov_b32_e32 v51, v182
	v_mov_b32_e32 v50, v181
	v_mov_b32_e32 v57, v180
	v_mov_b32_e32 v56, v179
	v_mov_b32_e32 v55, v178
	v_mov_b32_e32 v54, v177
	v_mov_b64_e32 v[44:45], v[34:35]
	v_mov_b64_e32 v[42:43], v[32:33]
	v_mov_b64_e32 v[48:49], v[30:31]
	v_mov_b64_e32 v[46:47], v[28:29]

.LBB0_1320:
	s_or_b64 exec, exec, s[0:1]
	s_cmp_lt_i32 s19, 8
	s_mov_b64 s[0:1], -1
	s_cbranch_scc1 .LBB0_1352
	s_cmp_lt_i32 s19, 12
	s_cbranch_scc1 .LBB0_1337
	s_cmp_lt_i32 s19, 14
	s_cbranch_scc1 .LBB0_1330
	s_cmp_lt_i32 s19, 15
	s_cbranch_scc1 .LBB0_1327
	s_cmp_eq_u32 s19, 15
	v_mov_b64_e32 v[28:29], v[46:47]
	v_mov_b64_e32 v[30:31], v[48:49]
	v_mov_b64_e32 v[32:33], v[42:43]
	v_mov_b64_e32 v[34:35], v[44:45]
	s_cbranch_scc0 .LBB0_1326
	v_mov_b32_e32 v28, v23
	v_mov_b32_e32 v29, v20
	v_mov_b32_e32 v30, v19
	v_mov_b32_e32 v31, v18
	v_mov_b32_e32 v32, v25
	v_mov_b32_e32 v33, v24
	v_mov_b32_e32 v34, v22
	v_mov_b32_e32 v35, v21

.LBB0_1327:
	s_andn2_b64 vcc, exec, s[0:1]
	v_mov_b32_e32 v177, v54
	v_mov_b32_e32 v178, v55
	v_mov_b32_e32 v179, v56
	v_mov_b32_e32 v180, v57
	v_mov_b32_e32 v181, v50
	v_mov_b32_e32 v182, v51
	v_mov_b32_e32 v183, v52
	v_mov_b32_e32 v184, v53
	s_cbranch_vccnz .LBB0_1329
	v_mov_b64_e32 v[28:29], v[46:47]
	v_mov_b64_e32 v[30:31], v[48:49]
	v_mov_b64_e32 v[32:33], v[42:43]
	v_mov_b64_e32 v[34:35], v[44:45]
	v_mov_b32_e32 v177, v23
	v_mov_b32_e32 v178, v20
	v_mov_b32_e32 v179, v19
	v_mov_b32_e32 v180, v18
	v_mov_b32_e32 v181, v25
	v_mov_b32_e32 v182, v24
	v_mov_b32_e32 v183, v22
	v_mov_b32_e32 v184, v21

.LBB0_1330:
	s_andn2_b64 vcc, exec, s[0:1]
	v_mov_b32_e32 v185, v62
	v_mov_b32_e32 v188, v63
	v_mov_b64_e32 v[200:201], v[64:65]
	v_mov_b64_e32 v[202:203], v[58:59]
	v_mov_b64_e32 v[204:205], v[60:61]
	v_mov_b64_e32 v[206:207], v[70:71]
	v_mov_b32_e32 v209, v72
	v_mov_b32_e32 v211, v73
	v_mov_b32_e32 v213, v66
	v_mov_b32_e32 v215, v67
	v_mov_b32_e32 v217, v68
	v_mov_b32_e32 v219, v69
	s_cbranch_vccnz .LBB0_1336
	s_cmp_gt_i32 s19, 12
	s_mov_b64 s[0:1], -1
	s_cbranch_scc0 .LBB0_1333
	s_mov_b64 s[0:1], 0
.LBB0_1333:
	s_andn2_b64 vcc, exec, s[0:1]
	v_mov_b32_e32 v185, v23
	v_mov_b32_e32 v188, v20
	v_mov_b32_e32 v200, v19
	v_mov_b32_e32 v201, v18
	v_mov_b32_e32 v202, v25
	v_mov_b32_e32 v203, v24
	v_mov_b32_e32 v204, v22
	v_mov_b32_e32 v205, v21
	v_mov_b64_e32 v[206:207], v[70:71]
	v_mov_b32_e32 v209, v72
	v_mov_b32_e32 v211, v73
	v_mov_b32_e32 v213, v66
	v_mov_b32_e32 v215, v67
	v_mov_b32_e32 v217, v68
	v_mov_b32_e32 v219, v69
	s_cbranch_vccnz .LBB0_1335
	v_mov_b32_e32 v185, v62
	v_mov_b32_e32 v188, v63
	v_mov_b64_e32 v[200:201], v[64:65]
	v_mov_b64_e32 v[202:203], v[58:59]
	v_mov_b64_e32 v[204:205], v[60:61]
	v_mov_b32_e32 v206, v23
	v_mov_b32_e32 v207, v20
	v_mov_b32_e32 v209, v19
	v_mov_b32_e32 v211, v18
	v_mov_b32_e32 v213, v25
	v_mov_b32_e32 v215, v24
	v_mov_b32_e32 v217, v22
	v_mov_b32_e32 v219, v21
.LBB0_1335:
	v_mov_b64_e32 v[28:29], v[46:47]
	v_mov_b64_e32 v[30:31], v[48:49]
	v_mov_b64_e32 v[32:33], v[42:43]
	v_mov_b64_e32 v[34:35], v[44:45]
	v_mov_b32_e32 v177, v54
	v_mov_b32_e32 v178, v55
	v_mov_b32_e32 v179, v56
	v_mov_b32_e32 v180, v57
	v_mov_b32_e32 v181, v50
	v_mov_b32_e32 v182, v51
	v_mov_b32_e32 v183, v52
	v_mov_b32_e32 v184, v53

.LBB0_1350:
	v_mov_b64_e32 v[28:29], v[46:47]
	v_mov_b64_e32 v[30:31], v[48:49]
	v_mov_b64_e32 v[32:33], v[42:43]
	v_mov_b64_e32 v[34:35], v[44:45]
	v_mov_b32_e32 v177, v54
	v_mov_b32_e32 v178, v55
	v_mov_b32_e32 v179, v56
	v_mov_b32_e32 v180, v57
	v_mov_b32_e32 v181, v50
	v_mov_b32_e32 v182, v51
	v_mov_b32_e32 v183, v52
	v_mov_b32_e32 v184, v53
	v_mov_b32_e32 v185, v62
	v_mov_b32_e32 v188, v63
	v_mov_b64_e32 v[200:201], v[64:65]
	v_mov_b64_e32 v[202:203], v[58:59]
	v_mov_b64_e32 v[204:205], v[60:61]
	v_mov_b64_e32 v[206:207], v[70:71]
	v_mov_b32_e32 v209, v72
	v_mov_b32_e32 v211, v73
	v_mov_b32_e32 v213, v66
	v_mov_b32_e32 v215, v67
	v_mov_b32_e32 v217, v68
	v_mov_b32_e32 v219, v69

.LBB0_1357:
	s_andn2_b64 vcc, exec, s[0:1]
	v_mov_b32_e32 v28, v23
	v_mov_b32_e32 v29, v20
	v_mov_b32_e32 v30, v19
	v_mov_b32_e32 v31, v18
	v_mov_b32_e32 v32, v25
	v_mov_b32_e32 v33, v24
	v_mov_b32_e32 v34, v22
	v_mov_b32_e32 v35, v21
	v_mov_b32_e32 v177, v119
	v_mov_b64_e32 v[178:179], v[120:121]
	v_mov_b32_e32 v180, v122
	v_mov_b32_e32 v181, v114
	v_mov_b32_e32 v182, v115
	v_mov_b32_e32 v183, v117
	v_mov_b32_e32 v184, v118
	s_cbranch_vccnz .LBB0_1359
	v_mov_b64_e32 v[28:29], v[110:111]
	v_mov_b64_e32 v[30:31], v[112:113]
	v_mov_b32_e32 v32, v105
	v_mov_b32_e32 v33, v107
	v_mov_b64_e32 v[34:35], v[108:109]
	v_mov_b32_e32 v177, v23
	v_mov_b32_e32 v178, v20
	v_mov_b32_e32 v179, v19
	v_mov_b32_e32 v180, v18
	v_mov_b32_e32 v181, v25
	v_mov_b32_e32 v182, v24
	v_mov_b32_e32 v183, v22
	v_mov_b32_e32 v184, v21

.LBB0_1365:
	v_mov_b64_e32 v[28:29], v[110:111]
	v_mov_b64_e32 v[30:31], v[112:113]
	v_mov_b32_e32 v32, v105
	v_mov_b32_e32 v33, v107
	v_mov_b64_e32 v[34:35], v[108:109]
	v_mov_b32_e32 v177, v119
	v_mov_b64_e32 v[178:179], v[120:121]
	v_mov_b32_e32 v180, v122
	v_mov_b32_e32 v181, v114
	v_mov_b32_e32 v182, v115
	v_mov_b32_e32 v183, v117
	v_mov_b32_e32 v184, v118

.LBB0_1371:
	s_andn2_b64 vcc, exec, s[0:1]
	v_mov_b32_e32 v28, v151
	v_mov_b32_e32 v29, v152
	v_mov_b32_e32 v30, v153
	v_mov_b32_e32 v31, v154
	v_mov_b32_e32 v32, v147
	v_mov_b32_e32 v33, v148
	v_mov_b32_e32 v34, v149
	v_mov_b32_e32 v35, v150
	v_mov_b32_e32 v177, v23
	v_mov_b32_e32 v178, v20
	v_mov_b32_e32 v179, v19
	v_mov_b32_e32 v180, v18
	v_mov_b32_e32 v181, v25
	v_mov_b32_e32 v182, v24
	v_mov_b32_e32 v183, v22
	v_mov_b32_e32 v184, v21
	s_cbranch_vccnz .LBB0_1373
	v_mov_b32_e32 v28, v23
	v_mov_b32_e32 v29, v20
	v_mov_b32_e32 v30, v19
	v_mov_b32_e32 v31, v18
	v_mov_b32_e32 v32, v25
	v_mov_b32_e32 v33, v24
	v_mov_b32_e32 v34, v22
	v_mov_b32_e32 v35, v21
	v_mov_b32_e32 v177, v143
	v_mov_b64_e32 v[178:179], v[144:145]
	v_mov_b32_e32 v180, v146
	v_mov_b32_e32 v181, v139
	v_mov_b64_e32 v[182:183], v[140:141]
	v_mov_b32_e32 v184, v142

.LBB0_1379:
	v_mov_b64_e32 v[110:111], v[28:29]
	v_mov_b64_e32 v[112:113], v[30:31]
	v_mov_b32_e32 v105, v32
	v_mov_b32_e32 v107, v33
	v_mov_b64_e32 v[108:109], v[34:35]
	v_mov_b32_e32 v119, v177
	v_mov_b64_e32 v[120:121], v[178:179]
	v_mov_b32_e32 v122, v180
	v_mov_b32_e32 v114, v181
	v_mov_b32_e32 v115, v182
	v_mov_b32_e32 v117, v183
	v_mov_b32_e32 v118, v184
	v_mov_b32_e32 v127, v185
	v_mov_b32_e32 v128, v188
	v_mov_b32_e32 v129, v200
	v_mov_b32_e32 v130, v202
	v_mov_b32_e32 v123, v204
	v_mov_b32_e32 v124, v206
	v_mov_b32_e32 v125, v208
	v_mov_b32_e32 v126, v209
	v_mov_b32_e32 v135, v210
	v_mov_b32_e32 v136, v211
	v_mov_b32_e32 v137, v212
	v_mov_b32_e32 v138, v213
	v_mov_b32_e32 v131, v201
	v_mov_b32_e32 v132, v203
	v_mov_b32_e32 v133, v205
	v_mov_b32_e32 v134, v207
	s_branch .LBB0_1295
.LBB0_1380:
	v_mov_b32_e32 v151, v28
	v_mov_b32_e32 v152, v29
	v_mov_b32_e32 v153, v30
	v_mov_b32_e32 v154, v31
	v_mov_b32_e32 v147, v32
	v_mov_b32_e32 v148, v33
	v_mov_b32_e32 v149, v34
	v_mov_b32_e32 v150, v35
	v_mov_b32_e32 v143, v177
	v_mov_b64_e32 v[144:145], v[178:179]
	v_mov_b32_e32 v146, v180
	v_mov_b32_e32 v139, v181
	v_mov_b64_e32 v[140:141], v[182:183]
	v_mov_b32_e32 v142, v184
	s_branch .LBB0_1295
